# cooperative-groups grid.sync after the weight-prep phase replaced by the kernel's own XCD-hierarchical barrier protocol (one L2 write-back per XCD, census completed here); bounded spins
# speedup vs baseline: 1.0020x; 1.0020x over previous
.LBB0_322:
	s_waitcnt vmcnt(0)
	s_barrier
	v_cmp_eq_u32_e32 vcc, 0, v208
	s_and_saveexec_b64 s[2:3], vcc
	s_cbranch_execz .LBB0_332
	s_waitcnt vmcnt(0) lgkmcnt(0)
	v_readlane_b32 s4, v254, 4
	v_readlane_b32 s5, v254, 5
	s_getreg_b32 s6, hwreg(HW_REG_XCC_ID, 0, 4)
	v_mov_b32_e32 v0, 0
	s_lshl_b32 s7, s6, 8
	s_add_u32 s8, s4, 0x400
	s_addc_u32 s9, s5, 0
	s_add_u32 s10, s8, s7
	s_addc_u32 s11, s9, 0
	s_mov_b32 m0, 0
.Lxs_census:
	global_load_dword v4, v0, s[8:9] sc1
	global_load_dword v5, v0, s[8:9] offset:256 sc1
	global_load_dword v6, v0, s[8:9] offset:512 sc1
	global_load_dword v7, v0, s[8:9] offset:768 sc1
	global_load_dword v8, v0, s[8:9] offset:1024 sc1
	global_load_dword v9, v0, s[8:9] offset:1280 sc1
	global_load_dword v10, v0, s[8:9] offset:1536 sc1
	global_load_dword v11, v0, s[8:9] offset:1792 sc1
	global_load_dword v12, v0, s[8:9] offset:2048 sc1
	global_load_dword v13, v0, s[8:9] offset:2304 sc1
	global_load_dword v14, v0, s[8:9] offset:2560 sc1
	global_load_dword v15, v0, s[8:9] offset:2816 sc1
	global_load_dword v16, v0, s[8:9] offset:3072 sc1
	global_load_dword v17, v0, s[8:9] offset:3328 sc1
	global_load_dword v18, v0, s[8:9] offset:3584 sc1
	global_load_dword v19, v0, s[8:9] offset:3840 sc1
	global_load_dword v20, v0, s[10:11] sc1
	s_waitcnt vmcnt(0)
	v_add_u32_e32 v21, v4, v5
	v_min_u32_e32 v22, 1, v4
	v_min_u32_e32 v23, 1, v5
	v_add_u32_e32 v22, v22, v23
	v_add_u32_e32 v21, v21, v6
	v_min_u32_e32 v23, 1, v6
	v_add_u32_e32 v22, v22, v23
	v_add_u32_e32 v21, v21, v7
	v_min_u32_e32 v23, 1, v7
	v_add_u32_e32 v22, v22, v23
	v_add_u32_e32 v21, v21, v8
	v_min_u32_e32 v23, 1, v8
	v_add_u32_e32 v22, v22, v23
	v_add_u32_e32 v21, v21, v9
	v_min_u32_e32 v23, 1, v9
	v_add_u32_e32 v22, v22, v23
	v_add_u32_e32 v21, v21, v10
	v_min_u32_e32 v23, 1, v10
	v_add_u32_e32 v22, v22, v23
	v_add_u32_e32 v21, v21, v11
	v_min_u32_e32 v23, 1, v11
	v_add_u32_e32 v22, v22, v23
	v_add_u32_e32 v21, v21, v12
	v_min_u32_e32 v23, 1, v12
	v_add_u32_e32 v22, v22, v23
	v_add_u32_e32 v21, v21, v13
	v_min_u32_e32 v23, 1, v13
	v_add_u32_e32 v22, v22, v23
	v_add_u32_e32 v21, v21, v14
	v_min_u32_e32 v23, 1, v14
	v_add_u32_e32 v22, v22, v23
	v_add_u32_e32 v21, v21, v15
	v_min_u32_e32 v23, 1, v15
	v_add_u32_e32 v22, v22, v23
	v_add_u32_e32 v21, v21, v16
	v_min_u32_e32 v23, 1, v16
	v_add_u32_e32 v22, v22, v23
	v_add_u32_e32 v21, v21, v17
	v_min_u32_e32 v23, 1, v17
	v_add_u32_e32 v22, v22, v23
	v_add_u32_e32 v21, v21, v18
	v_min_u32_e32 v23, 1, v18
	v_add_u32_e32 v22, v22, v23
	v_add_u32_e32 v21, v21, v19
	v_min_u32_e32 v23, 1, v19
	v_add_u32_e32 v22, v22, v23
	v_readfirstlane_b32 s100, v21
	v_readfirstlane_b32 s101, v22
	v_readfirstlane_b32 s7, v20
	s_nop 3
	s_cmp_eq_u32 s100, s94
	s_cbranch_scc1 .Lxs_census_done
	s_sleep 1
	s_add_u32 m0, m0, 1
	s_cmp_lt_u32 m0, 0x8000
	s_cbranch_scc1 .Lxs_census
.Lxs_census_done:
	v_mov_b32_e32 v1, 0x10c00
	v_mov_b32_e32 v2, s7
	v_mov_b32_e32 v3, s101
	ds_write2_b32 v1, v2, v3 offset1:1
	s_add_u32 s8, s10, 0x1000
	s_addc_u32 s9, s11, 0
	v_mov_b32_e32 v3, 1
	global_atomic_add v3, v0, v3, s[8:9] sc0
	s_add_u32 s10, s10, 0x2000
	s_addc_u32 s11, s11, 0
	s_mov_b32 m0, 0
	s_waitcnt vmcnt(0)
	v_readfirstlane_b32 s6, v3
	s_nop 3
	s_add_u32 s6, s6, 1
	s_cmp_eq_u32 s6, s7
	s_cbranch_scc0 .Lxs_follower
	buffer_wbl2 sc1
	s_waitcnt vmcnt(0)
	s_add_u32 s8, s4, 0x3400
	s_addc_u32 s9, s5, 0
	v_mov_b32_e32 v3, 1
	global_atomic_add v3, v0, v3, s[8:9] sc0
	s_waitcnt vmcnt(0)
	v_readfirstlane_b32 s6, v3
	s_nop 3
	s_add_u32 s6, s6, 1
	s_cmp_eq_u32 s6, s101
	v_mov_b32_e32 v3, 1
	s_cbranch_scc0 .Lxs_topwait
	global_atomic_add v0, v3, s[8:9] offset:256
	s_branch .Lxs_release
.Lxs_topwait:
	s_sleep 1
	global_load_dword v2, v0, s[8:9] offset:256 sc1
	s_waitcnt vmcnt(0)
	v_readfirstlane_b32 s6, v2
	s_add_u32 m0, m0, 1
	s_cmp_lg_u32 s6, 0
	s_cbranch_scc1 .Lxs_release
	s_cmp_lt_u32 m0, 0x8000
	s_cbranch_scc1 .Lxs_topwait
.Lxs_release:
	s_waitcnt vmcnt(0)
	buffer_inv sc1
	v_mov_b32_e32 v3, 1
	global_atomic_add v0, v3, s[10:11]
	s_waitcnt vmcnt(0)
	s_branch .Lxs_done
.Lxs_follower:
	s_sleep 1
	global_load_dword v2, v0, s[10:11] sc1
	s_waitcnt vmcnt(0)
	v_readfirstlane_b32 s6, v2
	s_add_u32 m0, m0, 1
	s_cmp_lg_u32 s6, 0
	s_cbranch_scc1 .Lxs_acq
	s_cmp_lt_u32 m0, 0x8000
	s_cbranch_scc1 .Lxs_follower
.Lxs_acq:
	buffer_inv sc1
	s_waitcnt vmcnt(0)
.Lxs_done:
	s_waitcnt lgkmcnt(0)
.LBB0_332:
	s_or_b64 exec, exec, s[2:3]
	s_mov_b64 s[10:11], s[58:59]
	v_readlane_b32 s2, v254, 0
	s_barrier
	.p2align 8
	s_and_b32 s4, 0xffff, s2
	s_load_dwordx2 s[2:3], s[10:11], 0x58
	s_load_dwordx2 s[6:7], s[10:11], 0xe0
	v_mov_b32_e32 v0, v208
	s_mul_i32 s5, s92, s4
	s_mul_i32 s4, s94, s4
	v_add_u32_e32 v0, s5, v0
	s_mov_b32 s5, 0xc000
	v_cmp_gt_i32_e32 vcc, s5, v0
	s_and_saveexec_b64 s[8:9], vcc
	v_readlane_b32 s35, v254, 2
	s_cbranch_execz .LBB0_337
	s_load_dwordx2 s[10:11], s[10:11], 0x20
	s_waitcnt lgkmcnt(0)
	s_add_u32 s12, s6, 0x9aa0000
	s_addc_u32 s13, s7, 0
	s_mov_b64 s[14:15], 0
	s_mov_b32 s18, 0x2aaaaaab
	s_movk_i32 s19, 0x1800
	s_mov_b32 s20, 0xbfff
	v_mov_b32_e32 v2, v0
